# P6 scan sweeps: two load groups in flight (unroll x2, alternate register set, counted vmcnt ladders) on top of carry-loop batching
# baseline (speedup 1.0000x reference)
; __device__ __forceinline__ unsigned cvt_pk_bf16(float lo, float hi) { unsigned r; asm volatile("v_cvt_pk_bf16_f32 %0, %1, %2" : "=v"(r) : "v"(lo), "v"(hi)); return r; }
; __device__ __forceinline__ float bf_lo(unsigned w) { return __uint_as_float(w << 16); }
; __device__ __forceinline__ float bf_hi(unsigned w) { return __uint_as_float(w & 0xffff0000u); }
; #define P6F_LOAD(W, g_) _Pragma("unroll") for (int s_ = 0; s_ < 8; ++s_) { const size_t tf_ = (size_t)(t0 + 8 * (g_) + s_); W[s_][0] = *(const unsigned*)(gp + tf_ * NG); W[s_][1] = *(const unsigned*)(gp + tf_ * NG + 256); }
; __global__ void __launch_bounds__(NWAVES * 64, 2) fwd(Args args) {
;     ...
;                 const int c = u >> 2, cb = u & 3, ch = cb * 1024 + tid * 2, hb = ch >> 8, jj = ch & 255, t0 = c * CHUNK;
;                 const int c_lo = (c / ncs) * ncs, c_hi = c_lo + ncs;
;                 const bf16_t* gp = GB + (size_t)hb * 1024 + jj; const bf16_t* yp = Z + ZC_Y + ch; bf16_t* ap = ALRU + ch;
;                 float hf0 = 0.f, hf1 = 0.f, hr0 = 0.f, hr1 = 0.f;
; #pragma unroll 4
;                 for (int cc = c_lo; cc < c; ++cc) { const f32x4 s = *(const f32x4*)(SUM + ((size_t)(cc * 2 + 0) * D + ch)); hf0 = s.x * hf0 + s.y; hf1 = s.z * hf1 + s.w; }
; #pragma unroll 4
;     ...
;                 { unsigned wn[8][2], wc_[8][2];
;     ...
;                   P6F_LOAD(wn, 0);
; #pragma unroll 1
;                   for (int g8 = 0; g8 < CHUNK / 8; ++g8) {
; #pragma unroll
;                     for (int s_ = 0; s_ < 8; ++s_) { wc_[s_][0] = wn[s_][0]; wc_[s_][1] = wn[s_][1]; }
;                     if (g8 + 1 < CHUNK / 8) { P6F_LOAD(wn, g8 + 1); }
; #pragma unroll
;                     for (int s_ = 0; s_ < 8; ++s_) { const size_t tf = (size_t)(t0 + 8 * g8 + s_);
;                         hf0 = __builtin_amdgcn_exp2f(bf_lo(wc_[s_][0])) * hf0 + bf_lo(wc_[s_][1]); hf1 = __builtin_amdgcn_exp2f(bf_hi(wc_[s_][0])) * hf1 + bf_hi(wc_[s_][1]);
;                         *(unsigned*)(ap + tf * D) = cvt_pk_bf16(hf0, hf1); }
;                   }
.LBB0_556:
	s_or_b64 exec, exec, s[34:35]
	v_ashrrev_i32_e32 v22, 8, v16
	v_lshlrev_b32_e32 v20, 7, v26
	v_ashrrev_i32_e32 v23, 31, v22
	v_lshlrev_b64 v[22:23], 11, v[22:23]
	v_ashrrev_i32_e32 v21, 31, v20
	v_lshl_add_u64 v[22:23], v[14:15], 0, v[22:23]
	v_lshlrev_b64 v[26:27], 15, v[20:21]
	v_lshl_add_u64 v[26:27], v[22:23], 0, v[26:27]
	global_load_dword v40, v[26:27], off
	global_load_dword v39, v[26:27], off offset:512
	v_or_b32_e32 v26, 1, v20
	v_ashrrev_i32_e32 v27, 31, v26
	v_lshlrev_b64 v[26:27], 15, v[26:27]
	v_lshl_add_u64 v[26:27], v[22:23], 0, v[26:27]
	global_load_dword v38, v[26:27], off
	global_load_dword v36, v[26:27], off offset:512
	v_or_b32_e32 v26, 2, v20
	v_ashrrev_i32_e32 v27, 31, v26
	v_lshlrev_b64 v[26:27], 15, v[26:27]
	v_and_b32_e32 v2, 0xc00, v33
	v_lshl_add_u64 v[26:27], v[22:23], 0, v[26:27]
	v_add_u32_e32 v28, v32, v2
	global_load_dword v37, v[26:27], off
	global_load_dword v2, v[26:27], off offset:512
	v_or_b32_e32 v26, 3, v20
	v_ashrrev_i32_e32 v27, 31, v26
	v_lshlrev_b64 v[26:27], 15, v[26:27]
	v_lshl_add_u64 v[26:27], v[22:23], 0, v[26:27]
	global_load_dword v41, v[26:27], off
	global_load_dword v43, v[26:27], off offset:512
	v_or_b32_e32 v26, 4, v20
	v_ashrrev_i32_e32 v27, 31, v26
	v_lshlrev_b64 v[26:27], 15, v[26:27]
	v_lshl_add_u64 v[26:27], v[22:23], 0, v[26:27]
	global_load_dword v45, v[26:27], off
	global_load_dword v46, v[26:27], off offset:512
	v_or_b32_e32 v26, 5, v20
	v_ashrrev_i32_e32 v27, 31, v26
	v_lshlrev_b64 v[26:27], 15, v[26:27]
	v_lshl_add_u64 v[26:27], v[22:23], 0, v[26:27]
	global_load_dword v47, v[26:27], off
	global_load_dword v48, v[26:27], off offset:512
	v_or_b32_e32 v26, 6, v20
	v_ashrrev_i32_e32 v27, 31, v26
	v_lshlrev_b64 v[26:27], 15, v[26:27]
	v_lshl_add_u64 v[26:27], v[22:23], 0, v[26:27]
	global_load_dword v51, v[26:27], off
	global_load_dword v52, v[26:27], off offset:512
	v_or_b32_e32 v26, 7, v20
	v_ashrrev_i32_e32 v27, 31, v26
	v_lshlrev_b64 v[26:27], 15, v[26:27]
	v_lshl_add_u64 v[26:27], v[22:23], 0, v[26:27]
	global_load_dword v55, v[26:27], off
	global_load_dword v56, v[26:27], off offset:512
	v_ashrrev_i32_e32 v29, 31, v28
	v_lshlrev_b64 v[26:27], 13, v[20:21]
	v_lshl_add_u64 v[26:27], v[28:29], 1, v[26:27]
	v_lshl_add_u64 v[28:29], v[10:11], 0, v[26:27]
	s_mov_b32 s9, 0
	s_waitcnt vmcnt(15)
	v_mov_b32_e32 v21, v40
	s_waitcnt vmcnt(14)
	v_mov_b32_e32 v44, v39
	s_waitcnt vmcnt(13)
	v_mov_b32_e32 v49, v38
	s_waitcnt vmcnt(12)
	v_mov_b32_e32 v50, v36
	s_waitcnt vmcnt(11)
	v_mov_b32_e32 v53, v37
	s_waitcnt vmcnt(10)
	v_mov_b32_e32 v54, v2
	s_waitcnt vmcnt(9)
	v_mov_b32_e32 v57, v41
	s_waitcnt vmcnt(8)
	v_mov_b32_e32 v58, v43
	s_waitcnt vmcnt(7)
	v_mov_b32_e32 v59, v45
	s_waitcnt vmcnt(6)
	v_mov_b32_e32 v60, v46
	s_waitcnt vmcnt(5)
	v_mov_b32_e32 v61, v47
	s_waitcnt vmcnt(4)
	v_mov_b32_e32 v62, v48
	s_waitcnt vmcnt(3)
	v_mov_b32_e32 v63, v51
	s_waitcnt vmcnt(2)
	v_mov_b32_e32 v64, v52
	s_waitcnt vmcnt(1)
	v_mov_b32_e32 v65, v55
	s_waitcnt vmcnt(0)
	v_mov_b32_e32 v66, v56
	v_add_u32_e32 v66, s9, v20
	v_add_u32_e32 v58, 8, v66
	v_ashrrev_i32_e32 v59, 31, v58
	v_lshlrev_b64 v[58:59], 15, v[58:59]
	v_lshl_add_u64 v[58:59], v[22:23], 0, v[58:59]
	global_load_dword v21, v[58:59], off
	global_load_dword v44, v[58:59], off offset:512
	v_add_u32_e32 v58, 9, v66
	v_ashrrev_i32_e32 v59, 31, v58
	v_lshlrev_b64 v[58:59], 15, v[58:59]
	v_lshl_add_u64 v[58:59], v[22:23], 0, v[58:59]
	global_load_dword v49, v[58:59], off
	global_load_dword v50, v[58:59], off offset:512
	v_add_u32_e32 v58, 10, v66
	v_ashrrev_i32_e32 v59, 31, v58
	v_lshlrev_b64 v[58:59], 15, v[58:59]
	v_lshl_add_u64 v[58:59], v[22:23], 0, v[58:59]
	global_load_dword v53, v[58:59], off
	global_load_dword v54, v[58:59], off offset:512
	v_add_u32_e32 v58, 11, v66
	v_add_u32_e32 v60, 12, v66
	v_add_u32_e32 v62, 13, v66
	v_add_u32_e32 v64, 14, v66
	v_add_u32_e32 v66, 15, v66
	v_ashrrev_i32_e32 v59, 31, v58
	v_ashrrev_i32_e32 v61, 31, v60
	v_ashrrev_i32_e32 v63, 31, v62
	v_ashrrev_i32_e32 v65, 31, v64
	v_ashrrev_i32_e32 v67, 31, v66
	v_lshlrev_b64 v[58:59], 15, v[58:59]
	v_lshlrev_b64 v[60:61], 15, v[60:61]
	v_lshlrev_b64 v[62:63], 15, v[62:63]
	v_lshlrev_b64 v[64:65], 15, v[64:65]
	v_lshlrev_b64 v[66:67], 15, v[66:67]
	v_lshl_add_u64 v[58:59], v[22:23], 0, v[58:59]
	v_lshl_add_u64 v[60:61], v[22:23], 0, v[60:61]
	v_lshl_add_u64 v[62:63], v[22:23], 0, v[62:63]
	v_lshl_add_u64 v[64:65], v[22:23], 0, v[64:65]
	v_lshl_add_u64 v[66:67], v[22:23], 0, v[66:67]
	global_load_dword v57, v[58:59], off
	s_nop 0
	global_load_dword v58, v[58:59], off offset:512
	s_nop 0
	global_load_dword v59, v[60:61], off
	s_nop 0
	global_load_dword v60, v[60:61], off offset:512
	s_nop 0
	global_load_dword v61, v[62:63], off
	s_nop 0
	global_load_dword v62, v[62:63], off offset:512
	s_nop 0
	global_load_dword v63, v[64:65], off
	s_nop 0
	global_load_dword v64, v[64:65], off offset:512
	s_nop 0
	global_load_dword v65, v[66:67], off
	s_nop 0
	global_load_dword v66, v[66:67], off offset:512
	global_load_dword v121, v[22:23], off
	global_load_dword v121, v[22:23], off
	global_load_dword v121, v[22:23], off
	global_load_dword v121, v[22:23], off
	global_load_dword v121, v[22:23], off
	global_load_dword v121, v[22:23], off
	global_load_dword v121, v[22:23], off
	global_load_dword v121, v[22:23], off
; __device__ __forceinline__ unsigned cvt_pk_bf16(float lo, float hi) { unsigned r; asm volatile("v_cvt_pk_bf16_f32 %0, %1, %2" : "=v"(r) : "v"(lo), "v"(hi)); return r; }
; __device__ __forceinline__ float bf_lo(unsigned w) { return __uint_as_float(w << 16); }
; __device__ __forceinline__ float bf_hi(unsigned w) { return __uint_as_float(w & 0xffff0000u); }
; #define P6F_LOAD(W, g_) _Pragma("unroll") for (int s_ = 0; s_ < 8; ++s_) { const size_t tf_ = (size_t)(t0 + 8 * (g_) + s_); W[s_][0] = *(const unsigned*)(gp + tf_ * NG); W[s_][1] = *(const unsigned*)(gp + tf_ * NG + 256); }
; __global__ void __launch_bounds__(NWAVES * 64, 2) fwd(Args args) {
;     ...
;                 { unsigned wn[8][2], wc_[8][2];
;     ...
;                   P6F_LOAD(wn, 0);
; #pragma unroll 1
;                   for (int g8 = 0; g8 < CHUNK / 8; ++g8) {
; #pragma unroll
;                     for (int s_ = 0; s_ < 8; ++s_) { wc_[s_][0] = wn[s_][0]; wc_[s_][1] = wn[s_][1]; }
;                     if (g8 + 1 < CHUNK / 8) { P6F_LOAD(wn, g8 + 1); }
; #pragma unroll
;                     for (int s_ = 0; s_ < 8; ++s_) { const size_t tf = (size_t)(t0 + 8 * g8 + s_);
;                         hf0 = __builtin_amdgcn_exp2f(bf_lo(wc_[s_][0])) * hf0 + bf_lo(wc_[s_][1]); hf1 = __builtin_amdgcn_exp2f(bf_hi(wc_[s_][0])) * hf1 + bf_hi(wc_[s_][1]);
;                         *(unsigned*)(ap + tf * D) = cvt_pk_bf16(hf0, hf1); }
;                   }
.Lfsw_top:
	v_add_u32_e32 v110, s9, v20
	v_add_u32_e32 v102, 16, v110
	v_ashrrev_i32_e32 v103, 31, v102
	v_lshlrev_b64 v[102:103], 15, v[102:103]
	v_lshl_add_u64 v[102:103], v[22:23], 0, v[102:103]
	global_load_dword v112, v[102:103], off
	global_load_dword v113, v[102:103], off offset:512
	v_add_u32_e32 v102, 17, v110
	v_ashrrev_i32_e32 v103, 31, v102
	v_lshlrev_b64 v[102:103], 15, v[102:103]
	v_lshl_add_u64 v[102:103], v[22:23], 0, v[102:103]
	global_load_dword v114, v[102:103], off
	global_load_dword v115, v[102:103], off offset:512
	v_add_u32_e32 v102, 18, v110
	v_ashrrev_i32_e32 v103, 31, v102
	v_lshlrev_b64 v[102:103], 15, v[102:103]
	v_lshl_add_u64 v[102:103], v[22:23], 0, v[102:103]
	global_load_dword v116, v[102:103], off
	global_load_dword v117, v[102:103], off offset:512
	v_add_u32_e32 v102, 19, v110
	v_add_u32_e32 v104, 20, v110
	v_add_u32_e32 v106, 21, v110
	v_add_u32_e32 v108, 22, v110
	v_add_u32_e32 v110, 23, v110
	v_ashrrev_i32_e32 v103, 31, v102
	v_ashrrev_i32_e32 v105, 31, v104
	v_ashrrev_i32_e32 v107, 31, v106
	v_ashrrev_i32_e32 v109, 31, v108
	v_ashrrev_i32_e32 v111, 31, v110
	v_lshlrev_b64 v[102:103], 15, v[102:103]
	v_lshlrev_b64 v[104:105], 15, v[104:105]
	v_lshlrev_b64 v[106:107], 15, v[106:107]
	v_lshlrev_b64 v[108:109], 15, v[108:109]
	v_lshlrev_b64 v[110:111], 15, v[110:111]
	v_lshl_add_u64 v[102:103], v[22:23], 0, v[102:103]
	v_lshl_add_u64 v[104:105], v[22:23], 0, v[104:105]
	v_lshl_add_u64 v[106:107], v[22:23], 0, v[106:107]
	v_lshl_add_u64 v[108:109], v[22:23], 0, v[108:109]
	v_lshl_add_u64 v[110:111], v[22:23], 0, v[110:111]
	global_load_dword v101, v[102:103], off
	s_nop 0
	global_load_dword v102, v[102:103], off offset:512
	s_nop 0
	global_load_dword v103, v[104:105], off
	s_nop 0
	global_load_dword v104, v[104:105], off offset:512
	s_nop 0
	global_load_dword v105, v[106:107], off
	s_nop 0
	global_load_dword v106, v[106:107], off offset:512
	s_nop 0
	global_load_dword v107, v[108:109], off
	s_nop 0
	global_load_dword v108, v[108:109], off offset:512
	s_nop 0
	global_load_dword v109, v[110:111], off
	s_nop 0
	global_load_dword v110, v[110:111], off offset:512
	v_lshlrev_b32_e32 v67, 16, v40
	v_exp_f32_e32 v67, v67
	v_and_b32_e32 v40, 0xffff0000, v40
	v_exp_f32_e32 v40, v40
	v_lshlrev_b32_e32 v68, 16, v39
	s_mov_b32 s15, 0xffff2000
	v_fmac_f32_e32 v68, v24, v67
	v_and_b32_e32 v39, 0xffff0000, v39
	v_add_co_u32_e32 v24, vcc, s15, v28
	v_fmac_f32_e32 v39, v25, v40
	s_nop 0
	v_addc_co_u32_e32 v25, vcc, -1, v29, vcc
	v_cvt_pk_bf16_f32 v40, v68, v39
	global_store_dword v[24:25], v40, off
	v_and_b32_e32 v25, 0xffff0000, v38
	v_exp_f32_e32 v25, v25
	v_lshlrev_b32_e32 v24, 16, v38
	v_exp_f32_e32 v24, v24
	v_and_b32_e32 v40, 0xffff0000, v36
	v_fmac_f32_e32 v40, v39, v25
	v_lshlrev_b32_e32 v39, 16, v37
	v_and_b32_e32 v37, 0xffff0000, v37
	v_exp_f32_e32 v37, v37
	v_lshlrev_b32_e32 v38, 16, v36
	s_mov_b32 s15, 0xffff4000
	v_exp_f32_e32 v39, v39
	v_fmac_f32_e32 v38, v68, v24
	v_add_co_u32_e32 v24, vcc, s15, v28
	v_cvt_pk_bf16_f32 v36, v38, v40
	v_lshlrev_b32_e32 v70, 16, v46
	s_nop 0
	v_addc_co_u32_e32 v25, vcc, -1, v29, vcc
	global_store_dword v[24:25], v36, off
	v_lshlrev_b32_e32 v36, 16, v2
	v_mul_f32_e32 v25, v40, v37
	v_and_b32_e32 v37, 0xffff0000, v2
	v_lshlrev_b32_e32 v2, 16, v41
	v_mul_f32_e32 v24, v38, v39
	v_exp_f32_e32 v38, v2
	v_and_b32_e32 v2, 0xffff0000, v41
	v_exp_f32_e32 v39, v2
	v_lshlrev_b32_e32 v2, 16, v45
	v_exp_f32_e32 v68, v2
	v_and_b32_e32 v2, 0xffff0000, v45
	v_exp_f32_e32 v69, v2
	v_lshlrev_b32_e32 v2, 16, v47
	v_and_b32_e32 v71, 0xffff0000, v46
	v_exp_f32_e32 v46, v2
	v_and_b32_e32 v2, 0xffff0000, v47
	v_exp_f32_e32 v47, v2
	v_lshlrev_b32_e32 v2, 16, v51
	v_exp_f32_e32 v74, v2
	v_and_b32_e32 v2, 0xffff0000, v51
	s_mov_b32 s15, 0xffff6000
	v_exp_f32_e32 v75, v2
	v_lshlrev_b32_e32 v2, 16, v55
	v_pk_add_f32 v[24:25], v[24:25], v[36:37]
	v_add_co_u32_e32 v36, vcc, s15, v28
	v_exp_f32_e32 v78, v2
	v_and_b32_e32 v2, 0xffff0000, v55
	v_addc_co_u32_e32 v37, vcc, -1, v29, vcc
	s_movk_i32 s15, 0x8000
	v_exp_f32_e32 v79, v2
	v_cvt_pk_bf16_f32 v2, v24, v25
	global_store_dword v[36:37], v2, off
	v_add_co_u32_e32 v36, vcc, s15, v28
	v_lshlrev_b32_e32 v40, 16, v43
	v_and_b32_e32 v41, 0xffff0000, v43
	v_addc_co_u32_e32 v37, vcc, -1, v29, vcc
	s_movk_i32 s15, 0xa000
	v_pk_fma_f32 v[24:25], v[24:25], v[38:39], v[40:41]
	v_lshlrev_b32_e32 v72, 16, v48
	v_cvt_pk_bf16_f32 v2, v24, v25
	global_store_dword v[36:37], v2, off
	v_add_co_u32_e32 v36, vcc, s15, v28
	s_movk_i32 s15, 0xc000
	s_nop 0
	v_addc_co_u32_e32 v37, vcc, -1, v29, vcc
	v_pk_fma_f32 v[24:25], v[24:25], v[68:69], v[70:71]
	v_and_b32_e32 v73, 0xffff0000, v48
	v_cvt_pk_bf16_f32 v2, v24, v25
	global_store_dword v[36:37], v2, off
	v_add_co_u32_e32 v36, vcc, s15, v28
	s_movk_i32 s15, 0xe000
	s_nop 0
	v_addc_co_u32_e32 v37, vcc, -1, v29, vcc
	v_lshlrev_b32_e32 v76, 16, v52
	v_and_b32_e32 v77, 0xffff0000, v52
	v_pk_fma_f32 v[24:25], v[24:25], v[46:47], v[72:73]
	v_lshlrev_b32_e32 v80, 16, v56
	v_cvt_pk_bf16_f32 v2, v24, v25
	global_store_dword v[36:37], v2, off
	v_add_co_u32_e32 v36, vcc, s15, v28
	v_and_b32_e32 v81, 0xffff0000, v56
	v_pk_fma_f32 v[24:25], v[24:25], v[74:75], v[76:77]
	v_addc_co_u32_e32 v37, vcc, -1, v29, vcc
	v_cvt_pk_bf16_f32 v2, v24, v25
	global_store_dword v[36:37], v2, off
	v_pk_fma_f32 v[24:25], v[24:25], v[78:79], v[80:81]
	s_add_i32 s9, s9, 8
	v_cvt_pk_bf16_f32 v2, v24, v25
	s_mov_b64 s[34:35], 0x10000
	global_store_dword v[28:29], v2, off
	v_lshl_add_u64 v[28:29], v[28:29], 0, s[34:35]
	s_cmpk_eq_i32 s9, 0x80
	s_waitcnt vmcnt(47)
	v_mov_b32_e32 v40, v21
	s_waitcnt vmcnt(46)
	v_mov_b32_e32 v39, v44
	s_waitcnt vmcnt(45)
; __device__ __forceinline__ unsigned cvt_pk_bf16(float lo, float hi) { unsigned r; asm volatile("v_cvt_pk_bf16_f32 %0, %1, %2" : "=v"(r) : "v"(lo), "v"(hi)); return r; }
; __device__ __forceinline__ float bf_lo(unsigned w) { return __uint_as_float(w << 16); }
; __device__ __forceinline__ float bf_hi(unsigned w) { return __uint_as_float(w & 0xffff0000u); }
; #define P6F_LOAD(W, g_) _Pragma("unroll") for (int s_ = 0; s_ < 8; ++s_) { const size_t tf_ = (size_t)(t0 + 8 * (g_) + s_); W[s_][0] = *(const unsigned*)(gp + tf_ * NG); W[s_][1] = *(const unsigned*)(gp + tf_ * NG + 256); }
; __global__ void __launch_bounds__(NWAVES * 64, 2) fwd(Args args) {
;     ...
;                 { unsigned wn[8][2], wc_[8][2];
;     ...
;                   P6F_LOAD(wn, 0);
; #pragma unroll 1
;                   for (int g8 = 0; g8 < CHUNK / 8; ++g8) {
; #pragma unroll
;                     for (int s_ = 0; s_ < 8; ++s_) { wc_[s_][0] = wn[s_][0]; wc_[s_][1] = wn[s_][1]; }
;                     if (g8 + 1 < CHUNK / 8) { P6F_LOAD(wn, g8 + 1); }
; #pragma unroll
;                     for (int s_ = 0; s_ < 8; ++s_) { const size_t tf = (size_t)(t0 + 8 * g8 + s_);
;                         hf0 = __builtin_amdgcn_exp2f(bf_lo(wc_[s_][0])) * hf0 + bf_lo(wc_[s_][1]); hf1 = __builtin_amdgcn_exp2f(bf_hi(wc_[s_][0])) * hf1 + bf_hi(wc_[s_][1]);
;                         *(unsigned*)(ap + tf * D) = cvt_pk_bf16(hf0, hf1); }
;                   }
	v_mov_b32_e32 v38, v49
	s_waitcnt vmcnt(44)
	v_mov_b32_e32 v36, v50
	s_waitcnt vmcnt(43)
	v_mov_b32_e32 v37, v53
	s_waitcnt vmcnt(42)
	v_mov_b32_e32 v2, v54
	s_waitcnt vmcnt(41)
	v_mov_b32_e32 v41, v57
	s_waitcnt vmcnt(40)
	v_mov_b32_e32 v43, v58
	s_waitcnt vmcnt(39)
	v_mov_b32_e32 v45, v59
	s_waitcnt vmcnt(38)
	v_mov_b32_e32 v46, v60
	s_waitcnt vmcnt(37)
	v_mov_b32_e32 v47, v61
	s_waitcnt vmcnt(36)
	v_mov_b32_e32 v48, v62
	s_waitcnt vmcnt(35)
	v_mov_b32_e32 v51, v63
	s_waitcnt vmcnt(34)
	v_mov_b32_e32 v52, v64
	s_waitcnt vmcnt(33)
	v_mov_b32_e32 v55, v65
	s_waitcnt vmcnt(32)
	v_mov_b32_e32 v56, v66
	v_add_u32_e32 v66, s9, v20
	v_add_u32_e32 v58, 16, v66
	v_ashrrev_i32_e32 v59, 31, v58
	v_lshlrev_b64 v[58:59], 15, v[58:59]
	v_lshl_add_u64 v[58:59], v[22:23], 0, v[58:59]
	global_load_dword v21, v[58:59], off
	global_load_dword v44, v[58:59], off offset:512
	v_add_u32_e32 v58, 17, v66
	v_ashrrev_i32_e32 v59, 31, v58
	v_lshlrev_b64 v[58:59], 15, v[58:59]
	v_lshl_add_u64 v[58:59], v[22:23], 0, v[58:59]
	global_load_dword v49, v[58:59], off
	global_load_dword v50, v[58:59], off offset:512
	v_add_u32_e32 v58, 18, v66
	v_ashrrev_i32_e32 v59, 31, v58
	v_lshlrev_b64 v[58:59], 15, v[58:59]
	v_lshl_add_u64 v[58:59], v[22:23], 0, v[58:59]
	global_load_dword v53, v[58:59], off
	global_load_dword v54, v[58:59], off offset:512
	v_add_u32_e32 v58, 19, v66
	v_add_u32_e32 v60, 20, v66
	v_add_u32_e32 v62, 21, v66
	v_add_u32_e32 v64, 22, v66
	v_add_u32_e32 v66, 23, v66
	v_ashrrev_i32_e32 v59, 31, v58
	v_ashrrev_i32_e32 v61, 31, v60
	v_ashrrev_i32_e32 v63, 31, v62
	v_ashrrev_i32_e32 v65, 31, v64
	v_ashrrev_i32_e32 v67, 31, v66
	v_lshlrev_b64 v[58:59], 15, v[58:59]
	v_lshlrev_b64 v[60:61], 15, v[60:61]
	v_lshlrev_b64 v[62:63], 15, v[62:63]
	v_lshlrev_b64 v[64:65], 15, v[64:65]
	v_lshlrev_b64 v[66:67], 15, v[66:67]
	v_lshl_add_u64 v[58:59], v[22:23], 0, v[58:59]
	v_lshl_add_u64 v[60:61], v[22:23], 0, v[60:61]
	v_lshl_add_u64 v[62:63], v[22:23], 0, v[62:63]
	v_lshl_add_u64 v[64:65], v[22:23], 0, v[64:65]
	v_lshl_add_u64 v[66:67], v[22:23], 0, v[66:67]
	global_load_dword v57, v[58:59], off
	s_nop 0
	global_load_dword v58, v[58:59], off offset:512
	s_nop 0
	global_load_dword v59, v[60:61], off
	s_nop 0
	global_load_dword v60, v[60:61], off offset:512
	s_nop 0
	global_load_dword v61, v[62:63], off
	s_nop 0
	global_load_dword v62, v[62:63], off offset:512
	s_nop 0
	global_load_dword v63, v[64:65], off
	s_nop 0
	global_load_dword v64, v[64:65], off offset:512
	s_nop 0
	global_load_dword v65, v[66:67], off
	s_nop 0
	global_load_dword v66, v[66:67], off offset:512
	v_lshlrev_b32_e32 v67, 16, v40
	v_exp_f32_e32 v67, v67
	v_and_b32_e32 v40, 0xffff0000, v40
	v_exp_f32_e32 v40, v40
	v_lshlrev_b32_e32 v68, 16, v39
	s_mov_b32 s15, 0xffff2000
	v_fmac_f32_e32 v68, v24, v67
	v_and_b32_e32 v39, 0xffff0000, v39
	v_add_co_u32_e32 v24, vcc, s15, v28
	v_fmac_f32_e32 v39, v25, v40
	s_nop 0
	v_addc_co_u32_e32 v25, vcc, -1, v29, vcc
	v_cvt_pk_bf16_f32 v40, v68, v39
	global_store_dword v[24:25], v40, off
	v_and_b32_e32 v25, 0xffff0000, v38
	v_exp_f32_e32 v25, v25
	v_lshlrev_b32_e32 v24, 16, v38
	v_exp_f32_e32 v24, v24
	v_and_b32_e32 v40, 0xffff0000, v36
	v_fmac_f32_e32 v40, v39, v25
	v_lshlrev_b32_e32 v39, 16, v37
	v_and_b32_e32 v37, 0xffff0000, v37
	v_exp_f32_e32 v37, v37
	v_lshlrev_b32_e32 v38, 16, v36
	s_mov_b32 s15, 0xffff4000
	v_exp_f32_e32 v39, v39
	v_fmac_f32_e32 v38, v68, v24
	v_add_co_u32_e32 v24, vcc, s15, v28
	v_cvt_pk_bf16_f32 v36, v38, v40
	v_lshlrev_b32_e32 v70, 16, v46
	s_nop 0
	v_addc_co_u32_e32 v25, vcc, -1, v29, vcc
	global_store_dword v[24:25], v36, off
	v_lshlrev_b32_e32 v36, 16, v2
	v_mul_f32_e32 v25, v40, v37
	v_and_b32_e32 v37, 0xffff0000, v2
	v_lshlrev_b32_e32 v2, 16, v41
	v_mul_f32_e32 v24, v38, v39
	v_exp_f32_e32 v38, v2
	v_and_b32_e32 v2, 0xffff0000, v41
	v_exp_f32_e32 v39, v2
	v_lshlrev_b32_e32 v2, 16, v45
	v_exp_f32_e32 v68, v2
	v_and_b32_e32 v2, 0xffff0000, v45
	v_exp_f32_e32 v69, v2
	v_lshlrev_b32_e32 v2, 16, v47
	v_and_b32_e32 v71, 0xffff0000, v46
	v_exp_f32_e32 v46, v2
	v_and_b32_e32 v2, 0xffff0000, v47
	v_exp_f32_e32 v47, v2
	v_lshlrev_b32_e32 v2, 16, v51
	v_exp_f32_e32 v74, v2
	v_and_b32_e32 v2, 0xffff0000, v51
	s_mov_b32 s15, 0xffff6000
	v_exp_f32_e32 v75, v2
	v_lshlrev_b32_e32 v2, 16, v55
	v_pk_add_f32 v[24:25], v[24:25], v[36:37]
	v_add_co_u32_e32 v36, vcc, s15, v28
	v_exp_f32_e32 v78, v2
	v_and_b32_e32 v2, 0xffff0000, v55
	v_addc_co_u32_e32 v37, vcc, -1, v29, vcc
	s_movk_i32 s15, 0x8000
	v_exp_f32_e32 v79, v2
	v_cvt_pk_bf16_f32 v2, v24, v25
	global_store_dword v[36:37], v2, off
	v_add_co_u32_e32 v36, vcc, s15, v28
	v_lshlrev_b32_e32 v40, 16, v43
	v_and_b32_e32 v41, 0xffff0000, v43
	v_addc_co_u32_e32 v37, vcc, -1, v29, vcc
	s_movk_i32 s15, 0xa000
	v_pk_fma_f32 v[24:25], v[24:25], v[38:39], v[40:41]
	v_lshlrev_b32_e32 v72, 16, v48
	v_cvt_pk_bf16_f32 v2, v24, v25
	global_store_dword v[36:37], v2, off
	v_add_co_u32_e32 v36, vcc, s15, v28
	s_movk_i32 s15, 0xc000
	s_nop 0
	v_addc_co_u32_e32 v37, vcc, -1, v29, vcc
	v_pk_fma_f32 v[24:25], v[24:25], v[68:69], v[70:71]
	v_and_b32_e32 v73, 0xffff0000, v48
	v_cvt_pk_bf16_f32 v2, v24, v25
	global_store_dword v[36:37], v2, off
	v_add_co_u32_e32 v36, vcc, s15, v28
	s_movk_i32 s15, 0xe000
	s_nop 0
	v_addc_co_u32_e32 v37, vcc, -1, v29, vcc
	v_lshlrev_b32_e32 v76, 16, v52
	v_and_b32_e32 v77, 0xffff0000, v52
	v_pk_fma_f32 v[24:25], v[24:25], v[46:47], v[72:73]
	v_lshlrev_b32_e32 v80, 16, v56
	v_cvt_pk_bf16_f32 v2, v24, v25
	global_store_dword v[36:37], v2, off
	v_add_co_u32_e32 v36, vcc, s15, v28
	v_and_b32_e32 v81, 0xffff0000, v56
	v_pk_fma_f32 v[24:25], v[24:25], v[74:75], v[76:77]
	v_addc_co_u32_e32 v37, vcc, -1, v29, vcc
	v_cvt_pk_bf16_f32 v2, v24, v25
	global_store_dword v[36:37], v2, off
	v_pk_fma_f32 v[24:25], v[24:25], v[78:79], v[80:81]
	s_add_i32 s9, s9, 8
	v_cvt_pk_bf16_f32 v2, v24, v25
	s_mov_b64 s[34:35], 0x10000
	global_store_dword v[28:29], v2, off
	v_lshl_add_u64 v[28:29], v[28:29], 0, s[34:35]
	s_cmpk_eq_i32 s9, 0x80
	s_waitcnt vmcnt(47)
	v_mov_b32_e32 v40, v112
	s_waitcnt vmcnt(46)
	v_mov_b32_e32 v39, v113
	s_waitcnt vmcnt(45)
	v_mov_b32_e32 v38, v114
	s_waitcnt vmcnt(44)
	v_mov_b32_e32 v36, v115
	s_waitcnt vmcnt(43)
	v_mov_b32_e32 v37, v116
	s_waitcnt vmcnt(42)
	v_mov_b32_e32 v2, v117
	s_waitcnt vmcnt(41)
	v_mov_b32_e32 v41, v101
	s_waitcnt vmcnt(40)
	v_mov_b32_e32 v43, v102
	s_waitcnt vmcnt(39)
	v_mov_b32_e32 v45, v103
	s_waitcnt vmcnt(38)
	v_mov_b32_e32 v46, v104
	s_waitcnt vmcnt(37)
	v_mov_b32_e32 v47, v105
	s_waitcnt vmcnt(36)
	v_mov_b32_e32 v48, v106
	s_waitcnt vmcnt(35)
	v_mov_b32_e32 v51, v107
	s_waitcnt vmcnt(34)
	v_mov_b32_e32 v52, v108
	s_waitcnt vmcnt(33)
	v_mov_b32_e32 v55, v109
	s_waitcnt vmcnt(32)
	v_mov_b32_e32 v56, v110
	s_cbranch_scc1 .Lfsw_exit
	s_branch .Lfsw_top

; #define P6R_LOAD(W, g_) _Pragma("unroll") for (int s_ = 0; s_ < 4; ++s_) { const size_t tr_ = (size_t)(t0 + CHUNK - 1 - 4 * (g_) - s_); W[s_][0] = *(const unsigned*)(gp + tr_ * NG + 512); W[s_][1] = *(const unsigned*)(gp + tr_ * NG + 768); \
;                     W[s_][2] = *(const unsigned*)(yp + tr_ * NZ); W[s_][3] = *(const unsigned*)(ap + tr_ * D); }
; __global__ void __launch_bounds__(NWAVES * 64, 2) fwd(Args args) {
;     ...
;                 { unsigned wn[4][4], wc_[4][4];
;     ...
;                   P6R_LOAD(wn, 0);
; #pragma unroll 1
;                   for (int g4 = 0; g4 < CHUNK / 4; ++g4) {
; #pragma unroll
;                     for (int s_ = 0; s_ < 4; ++s_)
; #pragma unroll
;                         for (int q_ = 0; q_ < 4; ++q_) wc_[s_][q_] = wn[s_][q_];
;                     if (g4 + 1 < CHUNK / 4) { P6R_LOAD(wn, g4 + 1); }
.LBB0_560:
	v_or_b32_e32 v36, 0x7f, v20
	v_ashrrev_i32_e32 v37, 31, v36
	v_lshlrev_b64 v[24:25], 1, v[16:17]
	v_lshlrev_b64 v[28:29], 15, v[36:37]
	v_lshl_add_u64 v[16:17], v[8:9], 0, v[24:25]
	v_lshl_add_u64 v[28:29], v[22:23], 0, v[28:29]
	v_lshl_add_u64 v[24:25], v[6:7], 0, v[24:25]
	global_load_dword v2, v[28:29], off offset:1024
	global_load_dword v21, v[28:29], off offset:1536
	v_mad_i64_i32 v[28:29], s[34:35], v36, s25, v[16:17]
	v_lshlrev_b64 v[36:37], 13, v[36:37]
	v_or_b32_e32 v40, 0x7e, v20
	v_lshl_add_u64 v[36:37], v[24:25], 0, v[36:37]
	v_ashrrev_i32_e32 v41, 31, v40
	global_load_dword v28, v[28:29], off
	v_or_b32_e32 v46, 0x7d, v20
	global_load_dword v29, v[36:37], off
	v_lshlrev_b64 v[36:37], 15, v[40:41]
	v_lshl_add_u64 v[38:39], v[22:23], 0, v[36:37]
	v_ashrrev_i32_e32 v47, 31, v46
	global_load_dword v36, v[38:39], off offset:1024
	global_load_dword v37, v[38:39], off offset:1536
	v_mad_i64_i32 v[38:39], s[34:35], v40, s25, v[16:17]
	v_lshlrev_b64 v[40:41], 13, v[40:41]
	v_lshlrev_b64 v[44:45], 15, v[46:47]
	v_or_b32_e32 v52, 0x7c, v20
	v_lshl_add_u64 v[40:41], v[24:25], 0, v[40:41]
	v_lshl_add_u64 v[44:45], v[22:23], 0, v[44:45]
	v_ashrrev_i32_e32 v53, 31, v52
	global_load_dword v38, v[38:39], off
	v_lshlrev_b64 v[48:49], 15, v[52:53]
	global_load_dword v40, v[40:41], off
	s_nop 0
	global_load_dword v41, v[44:45], off offset:1024
	global_load_dword v43, v[44:45], off offset:1536
	v_mad_i64_i32 v[44:45], s[34:35], v46, s25, v[16:17]
	v_lshlrev_b64 v[46:47], 13, v[46:47]
	v_mad_i64_i32 v[54:55], s[34:35], v52, s25, v[16:17]
	v_lshlrev_b64 v[52:53], 13, v[52:53]
	v_lshl_add_u64 v[46:47], v[24:25], 0, v[46:47]
	v_lshl_add_u64 v[50:51], v[22:23], 0, v[48:49]
	v_lshl_add_u64 v[52:53], v[24:25], 0, v[52:53]
	global_load_dword v45, v[44:45], off
	v_lshl_add_u64 v[26:27], v[12:13], 0, v[26:27]
	global_load_dword v47, v[46:47], off
	s_nop 0
	global_load_dword v48, v[50:51], off offset:1024
	s_nop 0
	global_load_dword v50, v[50:51], off offset:1536
	s_mov_b32 s9, 0
	global_load_dword v39, v[54:55], off
	global_load_dword v51, v[52:53], off
	s_waitcnt vmcnt(15)
	v_mov_b32_e32 v44, v2
	s_waitcnt vmcnt(14)
	v_mov_b32_e32 v46, v21
	s_waitcnt vmcnt(13)
	v_mov_b32_e32 v49, v28
	s_waitcnt vmcnt(12)
	v_mov_b32_e32 v52, v29
	s_waitcnt vmcnt(11)
	v_mov_b32_e32 v53, v36
	s_waitcnt vmcnt(10)
	v_mov_b32_e32 v54, v37
	s_waitcnt vmcnt(9)
	v_mov_b32_e32 v55, v38
	s_waitcnt vmcnt(8)
	v_mov_b32_e32 v56, v40
	s_waitcnt vmcnt(7)
	v_mov_b32_e32 v57, v41
	s_waitcnt vmcnt(6)
	v_mov_b32_e32 v58, v43
	s_waitcnt vmcnt(5)
	v_mov_b32_e32 v59, v45
	s_waitcnt vmcnt(4)
	v_mov_b32_e32 v60, v47
	s_waitcnt vmcnt(3)
	v_mov_b32_e32 v61, v48
	s_waitcnt vmcnt(2)
	v_mov_b32_e32 v62, v50
	s_waitcnt vmcnt(1)
	v_mov_b32_e32 v63, v39
	s_waitcnt vmcnt(0)
	v_mov_b32_e32 v64, v51
	v_add_u32_e32 v64, s9, v20
	v_add_u32_e32 v52, 0x7b, v64
	v_ashrrev_i32_e32 v53, 31, v52
	v_lshlrev_b64 v[54:55], 15, v[52:53]
	v_lshl_add_u64 v[54:55], v[22:23], 0, v[54:55]
	global_load_dword v44, v[54:55], off offset:1024
	global_load_dword v46, v[54:55], off offset:1536
	v_mad_i64_i32 v[54:55], s[34:35], v52, s25, v[16:17]
	v_lshlrev_b64 v[52:53], 13, v[52:53]
	v_add_u32_e32 v56, 0x7a, v64
	v_lshl_add_u64 v[52:53], v[24:25], 0, v[52:53]
	v_ashrrev_i32_e32 v57, 31, v56
	global_load_dword v49, v[54:55], off
	v_mad_i64_i32 v[58:59], s[34:35], v56, s25, v[16:17]
	global_load_dword v52, v[52:53], off
	v_lshlrev_b64 v[54:55], 15, v[56:57]
	v_lshlrev_b64 v[56:57], 13, v[56:57]
	v_add_u32_e32 v60, 0x79, v64
	v_lshl_add_u64 v[54:55], v[22:23], 0, v[54:55]
	v_lshl_add_u64 v[56:57], v[24:25], 0, v[56:57]
	v_ashrrev_i32_e32 v61, 31, v60
	global_load_dword v53, v[54:55], off offset:1024
	s_nop 0
	global_load_dword v54, v[54:55], off offset:1536
	v_mad_i64_i32 v[62:63], s[34:35], v60, s25, v[16:17]
	global_load_dword v55, v[58:59], off
	v_add_u32_e32 v64, 0x78, v64
	global_load_dword v56, v[56:57], off
	v_lshlrev_b64 v[58:59], 15, v[60:61]
	v_lshlrev_b64 v[60:61], 13, v[60:61]
	v_lshl_add_u64 v[58:59], v[22:23], 0, v[58:59]
	v_lshl_add_u64 v[60:61], v[24:25], 0, v[60:61]
	v_ashrrev_i32_e32 v65, 31, v64
	global_load_dword v57, v[58:59], off offset:1024
	s_nop 0
	global_load_dword v58, v[58:59], off offset:1536
	v_mad_i64_i32 v[66:67], s[34:35], v64, s25, v[16:17]
	global_load_dword v59, v[62:63], off
	s_nop 0
	global_load_dword v60, v[60:61], off
	v_lshlrev_b64 v[62:63], 15, v[64:65]
	v_lshlrev_b64 v[64:65], 13, v[64:65]
	v_lshl_add_u64 v[62:63], v[22:23], 0, v[62:63]
	v_lshl_add_u64 v[64:65], v[24:25], 0, v[64:65]
	global_load_dword v61, v[62:63], off offset:1024
	s_nop 0
	global_load_dword v62, v[62:63], off offset:1536
	s_nop 0
	global_load_dword v63, v[66:67], off
	s_nop 0
	global_load_dword v64, v[64:65], off
	global_load_dword v121, v[22:23], off
	global_load_dword v121, v[22:23], off
	global_load_dword v121, v[22:23], off
	global_load_dword v121, v[22:23], off
; __device__ __forceinline__ unsigned cvt_pk_bf16(float lo, float hi) { unsigned r; asm volatile("v_cvt_pk_bf16_f32 %0, %1, %2" : "=v"(r) : "v"(lo), "v"(hi)); return r; }
; __device__ __forceinline__ float bf_lo(unsigned w) { return __uint_as_float(w << 16); }
; __device__ __forceinline__ float bf_hi(unsigned w) { return __uint_as_float(w & 0xffff0000u); }
; #define P6R_LOAD(W, g_) _Pragma("unroll") for (int s_ = 0; s_ < 4; ++s_) { const size_t tr_ = (size_t)(t0 + CHUNK - 1 - 4 * (g_) - s_); W[s_][0] = *(const unsigned*)(gp + tr_ * NG + 512); W[s_][1] = *(const unsigned*)(gp + tr_ * NG + 768); \
;                     W[s_][2] = *(const unsigned*)(yp + tr_ * NZ); W[s_][3] = *(const unsigned*)(ap + tr_ * D); }
; __global__ void __launch_bounds__(NWAVES * 64, 2) fwd(Args args) {
;     ...
;                 { unsigned wn[4][4], wc_[4][4];
;     ...
;                   P6R_LOAD(wn, 0);
; #pragma unroll 1
;                   for (int g4 = 0; g4 < CHUNK / 4; ++g4) {
; #pragma unroll
;                     for (int s_ = 0; s_ < 4; ++s_)
; #pragma unroll
;                         for (int q_ = 0; q_ < 4; ++q_) wc_[s_][q_] = wn[s_][q_];
;                     if (g4 + 1 < CHUNK / 4) { P6R_LOAD(wn, g4 + 1); }
; #pragma unroll
;                     for (int s_ = 0; s_ < 4; ++s_) { const size_t tr = (size_t)(t0 + CHUNK - 1 - 4 * g4 - s_);
;                         hr0 = __builtin_amdgcn_exp2f(bf_lo(wc_[s_][0])) * hr0 + bf_lo(wc_[s_][1]); hr1 = __builtin_amdgcn_exp2f(bf_hi(wc_[s_][0])) * hr1 + bf_hi(wc_[s_][1]);
;                         *(unsigned*)(ap + tr * D) = cvt_pk_bf16((bf_lo(wc_[s_][3]) + hr0) * bf_lo(wc_[s_][2]), (bf_hi(wc_[s_][3]) + hr1) * bf_hi(wc_[s_][2])); }
;                   }
;     ...
;                 }
.Lrsw_top:
	v_add_u32_e32 v114, s9, v20
	v_add_u32_e32 v102, 0x77, v114
	v_ashrrev_i32_e32 v103, 31, v102
	v_lshlrev_b64 v[104:105], 15, v[102:103]
	v_lshl_add_u64 v[104:105], v[22:23], 0, v[104:105]
	global_load_dword v118, v[104:105], off offset:1024
	global_load_dword v119, v[104:105], off offset:1536
	v_mad_i64_i32 v[104:105], s[34:35], v102, s25, v[16:17]
	v_lshlrev_b64 v[102:103], 13, v[102:103]
	v_add_u32_e32 v106, 0x76, v114
	v_lshl_add_u64 v[102:103], v[24:25], 0, v[102:103]
	v_ashrrev_i32_e32 v107, 31, v106
	global_load_dword v120, v[104:105], off
	v_mad_i64_i32 v[108:109], s[34:35], v106, s25, v[16:17]
	global_load_dword v102, v[102:103], off
	v_lshlrev_b64 v[104:105], 15, v[106:107]
	v_lshlrev_b64 v[106:107], 13, v[106:107]
	v_add_u32_e32 v110, 0x75, v114
	v_lshl_add_u64 v[104:105], v[22:23], 0, v[104:105]
	v_lshl_add_u64 v[106:107], v[24:25], 0, v[106:107]
	v_ashrrev_i32_e32 v111, 31, v110
	global_load_dword v103, v[104:105], off offset:1024
	s_nop 0
	global_load_dword v104, v[104:105], off offset:1536
	v_mad_i64_i32 v[112:113], s[34:35], v110, s25, v[16:17]
	global_load_dword v105, v[108:109], off
	v_add_u32_e32 v114, 0x74, v114
	global_load_dword v106, v[106:107], off
	v_lshlrev_b64 v[108:109], 15, v[110:111]
	v_lshlrev_b64 v[110:111], 13, v[110:111]
	v_lshl_add_u64 v[108:109], v[22:23], 0, v[108:109]
	v_lshl_add_u64 v[110:111], v[24:25], 0, v[110:111]
	v_ashrrev_i32_e32 v115, 31, v114
	global_load_dword v107, v[108:109], off offset:1024
	s_nop 0
	global_load_dword v108, v[108:109], off offset:1536
	v_mad_i64_i32 v[116:117], s[34:35], v114, s25, v[16:17]
	global_load_dword v109, v[112:113], off
	s_nop 0
	global_load_dword v110, v[110:111], off
	v_lshlrev_b64 v[112:113], 15, v[114:115]
	v_lshlrev_b64 v[114:115], 13, v[114:115]
	v_lshl_add_u64 v[112:113], v[22:23], 0, v[112:113]
	v_lshl_add_u64 v[114:115], v[24:25], 0, v[114:115]
	global_load_dword v111, v[112:113], off offset:1024
	s_nop 0
	global_load_dword v112, v[112:113], off offset:1536
	s_nop 0
	global_load_dword v113, v[116:117], off
	s_nop 0
	global_load_dword v114, v[114:115], off
	v_lshlrev_b32_e32 v65, 16, v2
	v_and_b32_e32 v2, 0xffff0000, v2
	v_exp_f32_e32 v66, v65
	v_exp_f32_e32 v67, v2
	v_lshlrev_b32_e32 v68, 16, v21
	v_and_b32_e32 v69, 0xffff0000, v21
	v_lshlrev_b32_e32 v2, 16, v29
	v_lshlrev_b32_e32 v21, 16, v28
	v_and_b32_e32 v65, 0xffff0000, v29
	v_and_b32_e32 v76, 0xffff0000, v28
	v_lshlrev_b32_e32 v28, 16, v36
	v_and_b32_e32 v29, 0xffff0000, v36
	v_exp_f32_e32 v28, v28
	v_exp_f32_e32 v29, v29
	v_pk_fma_f32 v[18:19], v[18:19], v[66:67], v[68:69]
	v_lshlrev_b32_e32 v70, 16, v37
	v_and_b32_e32 v71, 0xffff0000, v37
	v_lshlrev_b32_e32 v36, 16, v41
	v_and_b32_e32 v37, 0xffff0000, v41
	v_add_f32_e32 v2, v18, v2
	s_movk_i32 s15, 0x6000
	v_exp_f32_e32 v36, v36
	v_exp_f32_e32 v37, v37
	v_mul_f32_e32 v2, v2, v21
	v_add_f32_e32 v21, v19, v65
	v_add_co_u32_e32 v66, vcc, s15, v26
	v_lshlrev_b32_e32 v77, 16, v40
	v_mul_f32_e32 v21, v21, v76
	v_cvt_pk_bf16_f32 v2, v2, v21
	v_addc_co_u32_e32 v67, vcc, 0, v27, vcc
	v_pk_fma_f32 v[18:19], v[18:19], v[28:29], v[70:71]
	v_lshlrev_b32_e32 v78, 16, v38
	v_and_b32_e32 v79, 0xffff0000, v40
	global_store_dword v[66:67], v2, off
	v_add_f32_e32 v2, v18, v77
	s_movk_i32 s15, 0x4000
	v_and_b32_e32 v38, 0xffff0000, v38
	v_lshlrev_b32_e32 v72, 16, v43
	v_and_b32_e32 v73, 0xffff0000, v43
	v_lshlrev_b32_e32 v40, 16, v48
	v_and_b32_e32 v41, 0xffff0000, v48
	v_mul_f32_e32 v2, v2, v78
	v_add_f32_e32 v21, v19, v79
	v_add_co_u32_e32 v28, vcc, s15, v26
	v_lshlrev_b32_e32 v43, 16, v47
	v_exp_f32_e32 v40, v40
	v_exp_f32_e32 v41, v41
	v_mul_f32_e32 v21, v21, v38
	v_cvt_pk_bf16_f32 v2, v2, v21
	v_addc_co_u32_e32 v29, vcc, 0, v27, vcc
	v_pk_fma_f32 v[18:19], v[18:19], v[36:37], v[72:73]
	v_lshlrev_b32_e32 v80, 16, v45
	v_and_b32_e32 v47, 0xffff0000, v47
	global_store_dword v[28:29], v2, off
	v_add_f32_e32 v2, v18, v43
	v_and_b32_e32 v45, 0xffff0000, v45
	v_mul_f32_e32 v2, v2, v80
	v_add_f32_e32 v21, v19, v47
	v_add_co_u32_e32 v28, vcc, s21, v26
	v_lshlrev_b32_e32 v74, 16, v50
	v_and_b32_e32 v75, 0xffff0000, v50
	v_mul_f32_e32 v21, v21, v45
	v_cvt_pk_bf16_f32 v2, v2, v21
	v_addc_co_u32_e32 v29, vcc, 0, v27, vcc
	global_store_dword v[28:29], v2, off
	v_pk_fma_f32 v[18:19], v[18:19], v[40:41], v[74:75]
	v_lshlrev_b32_e32 v2, 16, v51
	v_add_f32_e32 v2, v18, v2
	v_lshlrev_b32_e32 v21, 16, v39
	v_mul_f32_e32 v2, v2, v21
	v_and_b32_e32 v21, 0xffff0000, v51
	v_add_f32_e32 v21, v19, v21
	v_and_b32_e32 v28, 0xffff0000, v39
	s_movk_i32 s34, 0x8000
	v_mul_f32_e32 v21, v21, v28
	v_cvt_pk_bf16_f32 v2, v2, v21
	s_add_i32 s9, s9, -4
	s_mov_b32 s35, -1
	global_store_dword v[26:27], v2, off
	v_lshl_add_u64 v[26:27], v[26:27], 0, s[34:35]
	s_cmpk_eq_i32 s9, 0xff80
	s_waitcnt vmcnt(39)
	v_mov_b32_e32 v2, v44
	s_waitcnt vmcnt(38)
	v_mov_b32_e32 v21, v46
	s_waitcnt vmcnt(37)
	v_mov_b32_e32 v28, v49
	s_waitcnt vmcnt(36)
	v_mov_b32_e32 v29, v52
	s_waitcnt vmcnt(35)
	v_mov_b32_e32 v36, v53
	s_waitcnt vmcnt(34)
	v_mov_b32_e32 v37, v54
	s_waitcnt vmcnt(33)
	v_mov_b32_e32 v38, v55
	s_waitcnt vmcnt(32)
	v_mov_b32_e32 v40, v56
	s_waitcnt vmcnt(31)
	v_mov_b32_e32 v41, v57
	s_waitcnt vmcnt(30)
	v_mov_b32_e32 v43, v58
	s_waitcnt vmcnt(29)
	v_mov_b32_e32 v45, v59
	s_waitcnt vmcnt(28)
	v_mov_b32_e32 v47, v60
	s_waitcnt vmcnt(27)
	v_mov_b32_e32 v48, v61
	s_waitcnt vmcnt(26)
	v_mov_b32_e32 v50, v62
	s_waitcnt vmcnt(25)
	v_mov_b32_e32 v39, v63
	s_waitcnt vmcnt(24)
; __device__ __forceinline__ unsigned cvt_pk_bf16(float lo, float hi) { unsigned r; asm volatile("v_cvt_pk_bf16_f32 %0, %1, %2" : "=v"(r) : "v"(lo), "v"(hi)); return r; }
; __device__ __forceinline__ float bf_lo(unsigned w) { return __uint_as_float(w << 16); }
; __device__ __forceinline__ float bf_hi(unsigned w) { return __uint_as_float(w & 0xffff0000u); }
; #define P6R_LOAD(W, g_) _Pragma("unroll") for (int s_ = 0; s_ < 4; ++s_) { const size_t tr_ = (size_t)(t0 + CHUNK - 1 - 4 * (g_) - s_); W[s_][0] = *(const unsigned*)(gp + tr_ * NG + 512); W[s_][1] = *(const unsigned*)(gp + tr_ * NG + 768); \
;                     W[s_][2] = *(const unsigned*)(yp + tr_ * NZ); W[s_][3] = *(const unsigned*)(ap + tr_ * D); }
; __global__ void __launch_bounds__(NWAVES * 64, 2) fwd(Args args) {
;     ...
;                 { unsigned wn[4][4], wc_[4][4];
;     ...
;                   P6R_LOAD(wn, 0);
; #pragma unroll 1
;                   for (int g4 = 0; g4 < CHUNK / 4; ++g4) {
; #pragma unroll
;                     for (int s_ = 0; s_ < 4; ++s_)
; #pragma unroll
;                         for (int q_ = 0; q_ < 4; ++q_) wc_[s_][q_] = wn[s_][q_];
;                     if (g4 + 1 < CHUNK / 4) { P6R_LOAD(wn, g4 + 1); }
; #pragma unroll
;                     for (int s_ = 0; s_ < 4; ++s_) { const size_t tr = (size_t)(t0 + CHUNK - 1 - 4 * g4 - s_);
;                         hr0 = __builtin_amdgcn_exp2f(bf_lo(wc_[s_][0])) * hr0 + bf_lo(wc_[s_][1]); hr1 = __builtin_amdgcn_exp2f(bf_hi(wc_[s_][0])) * hr1 + bf_hi(wc_[s_][1]);
;                         *(unsigned*)(ap + tr * D) = cvt_pk_bf16((bf_lo(wc_[s_][3]) + hr0) * bf_lo(wc_[s_][2]), (bf_hi(wc_[s_][3]) + hr1) * bf_hi(wc_[s_][2])); }
;                   }
;     ...
;                 }
	v_mov_b32_e32 v51, v64
	v_add_u32_e32 v64, s9, v20
	v_add_u32_e32 v52, 0x77, v64
	v_ashrrev_i32_e32 v53, 31, v52
	v_lshlrev_b64 v[54:55], 15, v[52:53]
	v_lshl_add_u64 v[54:55], v[22:23], 0, v[54:55]
	global_load_dword v44, v[54:55], off offset:1024
	global_load_dword v46, v[54:55], off offset:1536
	v_mad_i64_i32 v[54:55], s[34:35], v52, s25, v[16:17]
	v_lshlrev_b64 v[52:53], 13, v[52:53]
	v_add_u32_e32 v56, 0x76, v64
	v_lshl_add_u64 v[52:53], v[24:25], 0, v[52:53]
	v_ashrrev_i32_e32 v57, 31, v56
	global_load_dword v49, v[54:55], off
	v_mad_i64_i32 v[58:59], s[34:35], v56, s25, v[16:17]
	global_load_dword v52, v[52:53], off
	v_lshlrev_b64 v[54:55], 15, v[56:57]
	v_lshlrev_b64 v[56:57], 13, v[56:57]
	v_add_u32_e32 v60, 0x75, v64
	v_lshl_add_u64 v[54:55], v[22:23], 0, v[54:55]
	v_lshl_add_u64 v[56:57], v[24:25], 0, v[56:57]
	v_ashrrev_i32_e32 v61, 31, v60
	global_load_dword v53, v[54:55], off offset:1024
	s_nop 0
	global_load_dword v54, v[54:55], off offset:1536
	v_mad_i64_i32 v[62:63], s[34:35], v60, s25, v[16:17]
	global_load_dword v55, v[58:59], off
	v_add_u32_e32 v64, 0x74, v64
	global_load_dword v56, v[56:57], off
	v_lshlrev_b64 v[58:59], 15, v[60:61]
	v_lshlrev_b64 v[60:61], 13, v[60:61]
	v_lshl_add_u64 v[58:59], v[22:23], 0, v[58:59]
	v_lshl_add_u64 v[60:61], v[24:25], 0, v[60:61]
	v_ashrrev_i32_e32 v65, 31, v64
	global_load_dword v57, v[58:59], off offset:1024
	s_nop 0
	global_load_dword v58, v[58:59], off offset:1536
	v_mad_i64_i32 v[66:67], s[34:35], v64, s25, v[16:17]
	global_load_dword v59, v[62:63], off
	s_nop 0
	global_load_dword v60, v[60:61], off
	v_lshlrev_b64 v[62:63], 15, v[64:65]
	v_lshlrev_b64 v[64:65], 13, v[64:65]
	v_lshl_add_u64 v[62:63], v[22:23], 0, v[62:63]
	v_lshl_add_u64 v[64:65], v[24:25], 0, v[64:65]
	global_load_dword v61, v[62:63], off offset:1024
	s_nop 0
	global_load_dword v62, v[62:63], off offset:1536
	s_nop 0
	global_load_dword v63, v[66:67], off
	s_nop 0
	global_load_dword v64, v[64:65], off
	v_lshlrev_b32_e32 v65, 16, v2
	v_and_b32_e32 v2, 0xffff0000, v2
	v_exp_f32_e32 v66, v65
	v_exp_f32_e32 v67, v2
	v_lshlrev_b32_e32 v68, 16, v21
	v_and_b32_e32 v69, 0xffff0000, v21
	v_lshlrev_b32_e32 v2, 16, v29
	v_lshlrev_b32_e32 v21, 16, v28
	v_and_b32_e32 v65, 0xffff0000, v29
	v_and_b32_e32 v76, 0xffff0000, v28
	v_lshlrev_b32_e32 v28, 16, v36
	v_and_b32_e32 v29, 0xffff0000, v36
	v_exp_f32_e32 v28, v28
	v_exp_f32_e32 v29, v29
	v_pk_fma_f32 v[18:19], v[18:19], v[66:67], v[68:69]
	v_lshlrev_b32_e32 v70, 16, v37
	v_and_b32_e32 v71, 0xffff0000, v37
	v_lshlrev_b32_e32 v36, 16, v41
	v_and_b32_e32 v37, 0xffff0000, v41
	v_add_f32_e32 v2, v18, v2
	s_movk_i32 s15, 0x6000
	v_exp_f32_e32 v36, v36
	v_exp_f32_e32 v37, v37
	v_mul_f32_e32 v2, v2, v21
	v_add_f32_e32 v21, v19, v65
	v_add_co_u32_e32 v66, vcc, s15, v26
	v_lshlrev_b32_e32 v77, 16, v40
	v_mul_f32_e32 v21, v21, v76
	v_cvt_pk_bf16_f32 v2, v2, v21
	v_addc_co_u32_e32 v67, vcc, 0, v27, vcc
	v_pk_fma_f32 v[18:19], v[18:19], v[28:29], v[70:71]
	v_lshlrev_b32_e32 v78, 16, v38
	v_and_b32_e32 v79, 0xffff0000, v40
	global_store_dword v[66:67], v2, off
	v_add_f32_e32 v2, v18, v77
	s_movk_i32 s15, 0x4000
	v_and_b32_e32 v38, 0xffff0000, v38
	v_lshlrev_b32_e32 v72, 16, v43
	v_and_b32_e32 v73, 0xffff0000, v43
	v_lshlrev_b32_e32 v40, 16, v48
	v_and_b32_e32 v41, 0xffff0000, v48
	v_mul_f32_e32 v2, v2, v78
	v_add_f32_e32 v21, v19, v79
	v_add_co_u32_e32 v28, vcc, s15, v26
	v_lshlrev_b32_e32 v43, 16, v47
	v_exp_f32_e32 v40, v40
	v_exp_f32_e32 v41, v41
	v_mul_f32_e32 v21, v21, v38
	v_cvt_pk_bf16_f32 v2, v2, v21
	v_addc_co_u32_e32 v29, vcc, 0, v27, vcc
	v_pk_fma_f32 v[18:19], v[18:19], v[36:37], v[72:73]
	v_lshlrev_b32_e32 v80, 16, v45
	v_and_b32_e32 v47, 0xffff0000, v47
	global_store_dword v[28:29], v2, off
	v_add_f32_e32 v2, v18, v43
	v_and_b32_e32 v45, 0xffff0000, v45
	v_mul_f32_e32 v2, v2, v80
	v_add_f32_e32 v21, v19, v47
	v_add_co_u32_e32 v28, vcc, s21, v26
	v_lshlrev_b32_e32 v74, 16, v50
	v_and_b32_e32 v75, 0xffff0000, v50
	v_mul_f32_e32 v21, v21, v45
	v_cvt_pk_bf16_f32 v2, v2, v21
	v_addc_co_u32_e32 v29, vcc, 0, v27, vcc
	global_store_dword v[28:29], v2, off
	v_pk_fma_f32 v[18:19], v[18:19], v[40:41], v[74:75]
	v_lshlrev_b32_e32 v2, 16, v51
	v_add_f32_e32 v2, v18, v2
	v_lshlrev_b32_e32 v21, 16, v39
	v_mul_f32_e32 v2, v2, v21
	v_and_b32_e32 v21, 0xffff0000, v51
	v_add_f32_e32 v21, v19, v21
	v_and_b32_e32 v28, 0xffff0000, v39
	s_movk_i32 s34, 0x8000
	v_mul_f32_e32 v21, v21, v28
	v_cvt_pk_bf16_f32 v2, v2, v21
	s_add_i32 s9, s9, -4
	s_mov_b32 s35, -1
	global_store_dword v[26:27], v2, off
	v_lshl_add_u64 v[26:27], v[26:27], 0, s[34:35]
	s_cmpk_eq_i32 s9, 0xff80
	s_waitcnt vmcnt(39)
	v_mov_b32_e32 v2, v118
	s_waitcnt vmcnt(38)
	v_mov_b32_e32 v21, v119
	s_waitcnt vmcnt(37)
	v_mov_b32_e32 v28, v120
	s_waitcnt vmcnt(36)
	v_mov_b32_e32 v29, v102
	s_waitcnt vmcnt(35)
	v_mov_b32_e32 v36, v103
	s_waitcnt vmcnt(34)
	v_mov_b32_e32 v37, v104
	s_waitcnt vmcnt(33)
	v_mov_b32_e32 v38, v105
	s_waitcnt vmcnt(32)
	v_mov_b32_e32 v40, v106
	s_waitcnt vmcnt(31)
	v_mov_b32_e32 v41, v107
	s_waitcnt vmcnt(30)
	v_mov_b32_e32 v43, v108
	s_waitcnt vmcnt(29)
	v_mov_b32_e32 v45, v109
	s_waitcnt vmcnt(28)
	v_mov_b32_e32 v47, v110
	s_waitcnt vmcnt(27)
	v_mov_b32_e32 v48, v111
	s_waitcnt vmcnt(26)
	v_mov_b32_e32 v50, v112
	s_waitcnt vmcnt(25)
	v_mov_b32_e32 v39, v113
	s_waitcnt vmcnt(24)
	v_mov_b32_e32 v51, v114
	s_cbranch_scc1 .Lrsw_exit
	s_branch .Lrsw_top
.Lrsw_exit:
	s_waitcnt vmcnt(0)
	s_branch .LBB0_535
